# v27 + redundant canonicalizing v_max removed before relu in the indexer scoring loop
# speedup vs baseline: 1.0038x; 1.0028x over previous
; #define MFMA32(a, b, c) __builtin_amdgcn_mfma_f32_32x32x16_bf16((a), (b), (c), 0, 0, 0)
; DI unsigned fkey(float f) { unsigned u = __float_as_uint(f); return (u & 0x80000000u) ? ~u : (u | 0x80000000u); }
; DI void dsa_index_phase(unsigned char* lds, KParamPtr P, int wv) {
;     ...
;     for (int kt0 = wave * 4; kt0 < ntile; kt0 += 32) {
;       bf16x8 kf[4][4];
;       const unsigned ko = (unsigned)((b * SEQ + kt0 * 32 + l31) * EIN + C_IK + hh * 8);
; #pragma unroll
;       for (int u = 0; u < 4; ++u)
; #pragma unroll
;         for (int ks = 0; ks < 4; ++ks) kf[u][ks] = ldg8(proj + ko + (unsigned)(u * 32 * EIN + ks * 16));
; #pragma unroll
;       for (int u = 0; u < 4; ++u) {
;         f32x16 acc = zero16();
; #pragma unroll
;         for (int ks = 0; ks < 4; ++ks) acc = MFMA32(af[ks], kf[u][ks], acc);
;         float s0 = 0.f, s1 = 0.f;
; #pragma unroll
;         for (int i = 0; i < 8; ++i) { s0 += w[i] * fmaxf(acc[i], 0.f); s1 += w[8 + i] * fmaxf(acc[8 + i], 0.f); }
;         const int key = (kt0 + u) * 32 + l31;
;         s0 += 0.f; s1 += 0.f;
;         sc[(2 * hh) * 8192 + key] = s0;
;         sc[(2 * hh + 1) * 8192 + key] = s1;
;         if (key <= t0 + 2 * hh) atomicAdd(hist + (2 * hh) * 256 + (fkey(s0) >> 24), 1u);
;         if (key <= t0 + 2 * hh + 1) atomicAdd(hist + (2 * hh + 1) * 256 + (fkey(s1) >> 24), 1u);
.LBB0_855:
	v_lshl_add_u64 v[38:39], v[0:1], 1, s[84:85]
	flat_load_dwordx4 v[2:5], v[38:39]
	flat_load_dwordx4 v[34:37], v[38:39] offset:1024
	flat_load_dwordx4 v[42:45], v[38:39] offset:2048
	flat_load_dwordx4 v[142:145], v[38:39] offset:3072
	v_add_co_u32_e32 v6, vcc, 0x1000, v38
	s_mov_b32 s2, 0x2000
	s_nop 0
	v_addc_co_u32_e32 v7, vcc, 0, v39, vcc
	flat_load_dwordx4 v[78:81], v[6:7]
	flat_load_dwordx4 v[74:77], v[6:7] offset:1024
	flat_load_dwordx4 v[70:73], v[6:7] offset:2048
	flat_load_dwordx4 v[66:69], v[6:7] offset:3072
	v_add_co_u32_e32 v40, vcc, s2, v38
	s_mov_b32 s2, 0x3000
	s_nop 0
	v_addc_co_u32_e32 v41, vcc, 0, v39, vcc
	v_add_co_u32_e32 v46, vcc, s2, v38
	flat_load_dwordx4 v[62:65], v[40:41]
	flat_load_dwordx4 v[54:57], v[40:41] offset:1024
	v_addc_co_u32_e32 v47, vcc, 0, v39, vcc
	flat_load_dwordx4 v[58:61], v[40:41] offset:2048
	flat_load_dwordx4 v[50:53], v[40:41] offset:3072
	v_cmp_le_i32_e32 vcc, v121, v120
	s_waitcnt vmcnt(0) lgkmcnt(0)
	v_mfma_f32_32x32x16_bf16 v[2:17], v[18:21], v[2:5], 0
	v_mfma_f32_32x32x16_bf16 v[2:17], v[22:25], v[34:37], v[2:17]
	flat_load_dwordx4 v[38:41], v[46:47]
	flat_load_dwordx4 v[34:37], v[46:47] offset:1024
	v_mfma_f32_32x32x16_bf16 v[2:17], v[26:29], v[42:45], v[2:17]
	flat_load_dwordx4 v[42:45], v[46:47] offset:2048
	s_nop 0
	flat_load_dwordx4 v[46:49], v[46:47] offset:3072
	v_mfma_f32_32x32x16_bf16 v[2:17], v[30:33], v[142:145], v[2:17]
	s_nop 11
	v_max_f32_e32 v2, 0, v2
	v_max_f32_e32 v10, 0, v10
	v_max_f32_e32 v3, 0, v3
	v_max_f32_e32 v11, 0, v11
	v_fma_f32 v2, v124, v2, 0
	v_fma_f32 v10, v132, v10, 0
	v_max_f32_e32 v4, 0, v4
	v_max_f32_e32 v12, 0, v12
	v_fmac_f32_e32 v2, v125, v3
	v_fmac_f32_e32 v10, v133, v11
	v_max_f32_e32 v5, 0, v5
	v_max_f32_e32 v13, 0, v13
	v_fmac_f32_e32 v2, v126, v4
	v_fmac_f32_e32 v10, v134, v12
	v_max_f32_e32 v6, 0, v6
	v_max_f32_e32 v14, 0, v14
	v_fmac_f32_e32 v2, v127, v5
	v_fmac_f32_e32 v10, v135, v13
	v_max_f32_e32 v7, 0, v7
	v_max_f32_e32 v15, 0, v15
	v_fmac_f32_e32 v2, v128, v6
	v_fmac_f32_e32 v10, v136, v14
	v_max_f32_e32 v8, 0, v8
	v_max_f32_e32 v16, 0, v16
	v_fmac_f32_e32 v2, v129, v7
	v_fmac_f32_e32 v10, v137, v15
	v_max_f32_e32 v9, 0, v9
	v_max_f32_e32 v17, 0, v17
	v_fmac_f32_e32 v2, v130, v8
	v_fmac_f32_e32 v10, v138, v16
	v_fmac_f32_e32 v2, v131, v9
	v_fmac_f32_e32 v10, v139, v17
	v_add_f32_e32 v3, 0, v2
	v_add_f32_e32 v2, 0, v10
	ds_write2st64_b32 v122, v3, v2 offset1:128
	s_and_saveexec_b64 s[22:23], vcc
	s_cbranch_execz .LBB0_857
	v_not_b32_e32 v4, v3
	v_or_b32_e32 v5, 0x80000000, v3
	v_cmp_gt_i32_e32 vcc, 0, v3
	s_nop 1
	v_cndmask_b32_e32 v3, v5, v4, vcc
	v_lshrrev_b32_e32 v3, 24, v3
	v_lshl_add_u32 v3, v3, 2, v99
	ds_add_u32 v3, v214

; #define MFMA32(a, b, c) __builtin_amdgcn_mfma_f32_32x32x16_bf16((a), (b), (c), 0, 0, 0)
; DI unsigned fkey(float f) { unsigned u = __float_as_uint(f); return (u & 0x80000000u) ? ~u : (u | 0x80000000u); }
; DI void dsa_index_phase(unsigned char* lds, KParamPtr P, int wv) {
;     ...
;       for (int u = 0; u < 4; ++u) {
;         f32x16 acc = zero16();
; #pragma unroll
;         for (int ks = 0; ks < 4; ++ks) acc = MFMA32(af[ks], kf[u][ks], acc);
;         float s0 = 0.f, s1 = 0.f;
; #pragma unroll
;         for (int i = 0; i < 8; ++i) { s0 += w[i] * fmaxf(acc[i], 0.f); s1 += w[8 + i] * fmaxf(acc[8 + i], 0.f); }
;         const int key = (kt0 + u) * 32 + l31;
;         s0 += 0.f; s1 += 0.f;
;         sc[(2 * hh) * 8192 + key] = s0;
;         sc[(2 * hh + 1) * 8192 + key] = s1;
;         if (key <= t0 + 2 * hh) atomicAdd(hist + (2 * hh) * 256 + (fkey(s0) >> 24), 1u);
;         if (key <= t0 + 2 * hh + 1) atomicAdd(hist + (2 * hh + 1) * 256 + (fkey(s1) >> 24), 1u);
.LBB0_859:
	s_or_b64 exec, exec, s[22:23]
	v_mfma_f32_32x32x16_bf16 v[2:17], v[18:21], v[78:81], 0
	v_mfma_f32_32x32x16_bf16 v[2:17], v[22:25], v[74:77], v[2:17]
	v_mfma_f32_32x32x16_bf16 v[2:17], v[26:29], v[70:73], v[2:17]
	v_mfma_f32_32x32x16_bf16 v[2:17], v[30:33], v[66:69], v[2:17]
	v_add_u32_e32 v66, 0x80, v122
	s_nop 10
	v_max_f32_e32 v2, 0, v2
	v_max_f32_e32 v3, 0, v3
	v_fma_f32 v2, v124, v2, 0
	v_max_f32_e32 v10, 0, v10
	v_max_f32_e32 v4, 0, v4
	v_fmac_f32_e32 v2, v125, v3
	v_max_f32_e32 v11, 0, v11
	v_max_f32_e32 v5, 0, v5
	v_fma_f32 v10, v132, v10, 0
	v_fmac_f32_e32 v2, v126, v4
	v_max_f32_e32 v12, 0, v12
	v_max_f32_e32 v6, 0, v6
	v_fmac_f32_e32 v10, v133, v11
	v_fmac_f32_e32 v2, v127, v5
	v_max_f32_e32 v13, 0, v13
	v_max_f32_e32 v7, 0, v7
	v_fmac_f32_e32 v10, v134, v12
	v_fmac_f32_e32 v2, v128, v6
	v_max_f32_e32 v3, v8, v8
	v_max_f32_e32 v14, 0, v14
	v_fmac_f32_e32 v10, v135, v13
	v_fmac_f32_e32 v2, v129, v7
	v_max_f32_e32 v3, 0, v3
	v_max_f32_e32 v15, 0, v15
	v_fmac_f32_e32 v10, v136, v14
	v_fmac_f32_e32 v2, v130, v3
	v_max_f32_e32 v3, v16, v16
	v_fmac_f32_e32 v10, v137, v15
	v_max_f32_e32 v3, 0, v3
	v_fmac_f32_e32 v10, v138, v3
	v_max_f32_e32 v3, v9, v9
	v_max_f32_e32 v3, 0, v3
	v_fmac_f32_e32 v2, v131, v3
	v_max_f32_e32 v3, v17, v17
	v_max_f32_e32 v3, 0, v3
	v_fmac_f32_e32 v10, v139, v3
	v_add_u32_e32 v3, 32, v121
	v_add_f32_e32 v4, 0, v2
	v_add_f32_e32 v2, 0, v10
	v_cmp_le_i32_e32 vcc, v3, v120
	ds_write2st64_b32 v66, v4, v2 offset1:128
	s_and_saveexec_b64 s[22:23], vcc
	s_cbranch_execz .LBB0_861
	v_not_b32_e32 v5, v4
	v_or_b32_e32 v6, 0x80000000, v4
	v_cmp_gt_i32_e32 vcc, 0, v4
	s_nop 1
	v_cndmask_b32_e32 v4, v6, v5, vcc
	v_lshrrev_b32_e32 v4, 24, v4
	v_lshl_add_u32 v4, v4, 2, v99
	ds_add_u32 v4, v214

; #define MFMA32(a, b, c) __builtin_amdgcn_mfma_f32_32x32x16_bf16((a), (b), (c), 0, 0, 0)
; DI unsigned fkey(float f) { unsigned u = __float_as_uint(f); return (u & 0x80000000u) ? ~u : (u | 0x80000000u); }
; DI void dsa_index_phase(unsigned char* lds, KParamPtr P, int wv) {
;     ...
;       for (int u = 0; u < 4; ++u) {
;         f32x16 acc = zero16();
; #pragma unroll
;         for (int ks = 0; ks < 4; ++ks) acc = MFMA32(af[ks], kf[u][ks], acc);
;         float s0 = 0.f, s1 = 0.f;
; #pragma unroll
;         for (int i = 0; i < 8; ++i) { s0 += w[i] * fmaxf(acc[i], 0.f); s1 += w[8 + i] * fmaxf(acc[8 + i], 0.f); }
;         const int key = (kt0 + u) * 32 + l31;
;         s0 += 0.f; s1 += 0.f;
;         sc[(2 * hh) * 8192 + key] = s0;
;         sc[(2 * hh + 1) * 8192 + key] = s1;
;         if (key <= t0 + 2 * hh) atomicAdd(hist + (2 * hh) * 256 + (fkey(s0) >> 24), 1u);
;         if (key <= t0 + 2 * hh + 1) atomicAdd(hist + (2 * hh + 1) * 256 + (fkey(s1) >> 24), 1u);
.LBB0_863:
	s_or_b64 exec, exec, s[22:23]
	v_mfma_f32_32x32x16_bf16 v[2:17], v[18:21], v[62:65], 0
	v_mfma_f32_32x32x16_bf16 v[2:17], v[22:25], v[54:57], v[2:17]
	v_mfma_f32_32x32x16_bf16 v[2:17], v[26:29], v[58:61], v[2:17]
	v_mfma_f32_32x32x16_bf16 v[2:17], v[30:33], v[50:53], v[2:17]
	s_nop 11
	v_max_f32_e32 v2, 0, v2
	v_max_f32_e32 v3, 0, v3
	v_fma_f32 v2, v124, v2, 0
	v_max_f32_e32 v10, 0, v10
	v_max_f32_e32 v4, 0, v4
	v_fmac_f32_e32 v2, v125, v3
	v_max_f32_e32 v11, 0, v11
	v_max_f32_e32 v5, 0, v5
	v_fma_f32 v10, v132, v10, 0
	v_fmac_f32_e32 v2, v126, v4
	v_max_f32_e32 v12, 0, v12
	v_max_f32_e32 v6, 0, v6
	v_fmac_f32_e32 v10, v133, v11
	v_fmac_f32_e32 v2, v127, v5
	v_max_f32_e32 v13, 0, v13
	v_max_f32_e32 v7, 0, v7
	v_fmac_f32_e32 v10, v134, v12
	v_fmac_f32_e32 v2, v128, v6
	v_max_f32_e32 v3, v8, v8
	v_max_f32_e32 v14, 0, v14
	v_fmac_f32_e32 v10, v135, v13
	v_fmac_f32_e32 v2, v129, v7
	v_max_f32_e32 v3, 0, v3
	v_max_f32_e32 v15, 0, v15
	v_fmac_f32_e32 v10, v136, v14
	v_fmac_f32_e32 v2, v130, v3
	v_max_f32_e32 v3, v16, v16
	v_fmac_f32_e32 v10, v137, v15
	v_max_f32_e32 v3, 0, v3
	v_fmac_f32_e32 v10, v138, v3
	v_max_f32_e32 v3, v9, v9
	v_max_f32_e32 v3, 0, v3
	v_fmac_f32_e32 v2, v131, v3
	v_max_f32_e32 v3, v17, v17
	v_max_f32_e32 v3, 0, v3
	v_fmac_f32_e32 v10, v139, v3
	v_add_u32_e32 v3, 64, v121
	v_add_f32_e32 v4, 0, v2
	v_add_f32_e32 v2, 0, v10
	v_cmp_le_i32_e32 vcc, v3, v120
	ds_write2st64_b32 v122, v4, v2 offset0:1 offset1:129
	s_and_saveexec_b64 s[22:23], vcc
	s_cbranch_execz .LBB0_865
	v_not_b32_e32 v5, v4
	v_or_b32_e32 v6, 0x80000000, v4
	v_cmp_gt_i32_e32 vcc, 0, v4
	s_nop 1
	v_cndmask_b32_e32 v4, v6, v5, vcc
	v_lshrrev_b32_e32 v4, 24, v4
	v_lshl_add_u32 v4, v4, 2, v99
	ds_add_u32 v4, v214

; #define MFMA32(a, b, c) __builtin_amdgcn_mfma_f32_32x32x16_bf16((a), (b), (c), 0, 0, 0)
; DI unsigned fkey(float f) { unsigned u = __float_as_uint(f); return (u & 0x80000000u) ? ~u : (u | 0x80000000u); }
; DI void dsa_index_phase(unsigned char* lds, KParamPtr P, int wv) {
;     ...
;       for (int u = 0; u < 4; ++u) {
;         f32x16 acc = zero16();
; #pragma unroll
;         for (int ks = 0; ks < 4; ++ks) acc = MFMA32(af[ks], kf[u][ks], acc);
;         float s0 = 0.f, s1 = 0.f;
; #pragma unroll
;         for (int i = 0; i < 8; ++i) { s0 += w[i] * fmaxf(acc[i], 0.f); s1 += w[8 + i] * fmaxf(acc[8 + i], 0.f); }
;         const int key = (kt0 + u) * 32 + l31;
;         s0 += 0.f; s1 += 0.f;
;         sc[(2 * hh) * 8192 + key] = s0;
;         sc[(2 * hh + 1) * 8192 + key] = s1;
;         if (key <= t0 + 2 * hh) atomicAdd(hist + (2 * hh) * 256 + (fkey(s0) >> 24), 1u);
;         if (key <= t0 + 2 * hh + 1) atomicAdd(hist + (2 * hh + 1) * 256 + (fkey(s1) >> 24), 1u);
.LBB0_867:
	s_or_b64 exec, exec, s[22:23]
	s_waitcnt vmcnt(0) lgkmcnt(0)
	v_mfma_f32_32x32x16_bf16 v[2:17], v[18:21], v[38:41], 0
	v_mfma_f32_32x32x16_bf16 v[2:17], v[22:25], v[34:37], v[2:17]
	v_mfma_f32_32x32x16_bf16 v[2:17], v[26:29], v[42:45], v[2:17]
	v_mfma_f32_32x32x16_bf16 v[2:17], v[30:33], v[46:49], v[2:17]
	s_nop 11
	v_max_f32_e32 v2, 0, v2
	v_max_f32_e32 v3, 0, v3
	v_fma_f32 v2, v124, v2, 0
	v_max_f32_e32 v10, 0, v10
	v_max_f32_e32 v4, 0, v4
	v_fmac_f32_e32 v2, v125, v3
	v_max_f32_e32 v11, 0, v11
	v_max_f32_e32 v5, 0, v5
	v_fma_f32 v10, v132, v10, 0
	v_fmac_f32_e32 v2, v126, v4
	v_max_f32_e32 v12, 0, v12
	v_max_f32_e32 v6, 0, v6
	v_fmac_f32_e32 v10, v133, v11
	v_fmac_f32_e32 v2, v127, v5
	v_max_f32_e32 v13, 0, v13
	v_max_f32_e32 v7, 0, v7
	v_fmac_f32_e32 v10, v134, v12
	v_fmac_f32_e32 v2, v128, v6
	v_max_f32_e32 v3, v8, v8
	v_max_f32_e32 v14, 0, v14
	v_fmac_f32_e32 v10, v135, v13
	v_fmac_f32_e32 v2, v129, v7
	v_max_f32_e32 v3, 0, v3
	v_max_f32_e32 v15, 0, v15
	v_fmac_f32_e32 v10, v136, v14
	v_fmac_f32_e32 v2, v130, v3
	v_max_f32_e32 v3, v16, v16
	v_fmac_f32_e32 v10, v137, v15
	v_max_f32_e32 v3, 0, v3
	v_fmac_f32_e32 v10, v138, v3
	v_max_f32_e32 v3, v9, v9
	v_max_f32_e32 v3, 0, v3
	v_fmac_f32_e32 v2, v131, v3
	v_max_f32_e32 v3, v17, v17
	v_max_f32_e32 v3, 0, v3
	v_fmac_f32_e32 v10, v139, v3
	v_add_u32_e32 v3, 0x60, v121
	v_add_f32_e32 v4, 0, v2
	v_add_f32_e32 v2, 0, v10
	v_cmp_le_i32_e32 vcc, v3, v120
	ds_write2st64_b32 v66, v4, v2 offset0:1 offset1:129
	s_and_saveexec_b64 s[22:23], vcc
	s_cbranch_execz .LBB0_869
	v_not_b32_e32 v5, v4
	v_or_b32_e32 v6, 0x80000000, v4
	v_cmp_gt_i32_e32 vcc, 0, v4
	s_nop 1
	v_cndmask_b32_e32 v4, v6, v5, vcc
	v_lshrrev_b32_e32 v4, 24, v4
	v_lshl_add_u32 v4, v4, 2, v99
	ds_add_u32 v4, v214
